# static priority raise for waves 4..7 during attention A and B
# speedup vs baseline: 1.0017x; 1.0017x over previous
.LBB0_335:
	s_cmp_lt_i32 s88, 3
	s_cselect_b64 s[4:5], -1, 0
	s_and_b64 s[2:3], s[4:5], s[2:3]
	s_andn2_b64 vcc, exec, s[2:3]
	s_cbranch_vccnz .LBB0_403
	v_lshrrev_b32_e32 v182, 5, v214
	s_waitcnt lgkmcnt(0)
	v_lshrrev_b32_e32 v4, 1, v215
	v_readlane_b32 s4, v243, 16
	v_bitop3_b32 v4, v182, v4, 7 bitop3:0x78
	s_lshl_b32 s40, s92, 5
	s_lshr_b32 s41, s4, 7
	v_mul_u32_u24_e32 v0, 0xc00, v178
	v_lshlrev_b32_e32 v3, 3, v182
	v_lshlrev_b32_e32 v2, 3, v215
	v_lshlrev_b32_e32 v173, 4, v4
	v_lshlrev_b32_e32 v4, 1, v215
	s_cmpk_gt_i32 s33, 0xff
	v_mov_b32_e32 v1, 0
	s_movk_i32 s42, 0xc00
	v_lshrrev_b32_e32 v172, 3, v214
	v_bfe_u32 v183, v215, 2, 2
	v_lshlrev_b32_e32 v174, 7, v178
	v_and_b32_e32 v175, 32, v4
	v_and_b32_e32 v176, 24, v2
	v_xor_b32_e32 v177, 32, v173
	v_xor_b32_e32 v179, 64, v173
	v_xor_b32_e32 v180, 0x60, v173
	v_lshlrev_b32_e32 v181, 2, v182
	v_lshlrev_b32_e32 v132, 1, v0
	v_lshlrev_b32_e32 v134, 1, v3
	s_cbranch_scc1 .LBB0_377
	v_mov_b32_e32 v0, 0x184000
	global_load_dword v136, v0, s[50:51]
	v_lshrrev_b32_e32 v184, 4, v214
	v_lshlrev_b32_e32 v0, 2, v181
	v_and_b32_e32 v3, 0x78, v2
	v_lshlrev_b32_e32 v5, 5, v184
	v_lshl_add_u64 v[144:145], s[64:65], 0, v[0:1]
	v_mul_u32_u24_e32 v0, 0xc00, v184
	s_movk_i32 s4, 0x78
	s_movk_i32 s24, 0x3000
	v_lshlrev_b32_e32 v187, 6, v183
	v_mbcnt_lo_u32_b32 v4, -1, 0
	v_bitop3_b32 v196, v5, v0, v3 bitop3:0xde
	v_lshlrev_b32_e32 v185, 10, v182
	v_lshlrev_b32_e32 v186, 8, v183
	v_mul_u32_u24_e32 v188, 0xc00, v172
	s_mov_b32 s5, 0
	s_mov_b64 s[6:7], 0x400
	s_mov_b64 s[12:13], 0x800
	v_mov_b32_e32 v133, v1
	v_mov_b32_e32 v135, v1
	s_mov_b64 s[14:15], 0x60000
	s_mov_b64 s[16:17], 0xc0000
	s_mov_b32 s43, 0x3e38aa3b
	s_cmp_lt_u32 s92, 4
	s_cbranch_scc1 .La_prio_skip
	s_setprio 1
.La_prio_skip:
	s_mov_b64 s[18:19], 0x480
	s_mov_b64 s[20:21], 0x60080
	s_mov_b64 s[22:23], 0xc0080
	v_mov_b32_e32 v189, 0x358637bd
	v_mov_b64_e32 v[138:139], 0x8520800
	v_mov_b64_e32 v[140:141], 0x8520400
	v_mov_b64_e32 v[142:143], 0x8520480
	v_xor_b32_e32 v190, 64, v187
	v_xor_b32_e32 v191, 0x80, v187
	v_xor_b32_e32 v192, 0xc0, v187
	v_add3_u32 v199, v185, v186, v175
	v_add_u32_e32 v199, v199, v176
	v_mbcnt_hi_u32_b32 v193, -1, v4
	v_bitop3_b32 v194, v5, v2, s4 bitop3:0x78
	v_bitop3_b32 v195, v5, s24, v3 bitop3:0xde
	v_add_u32_e32 v197, 0x3000, v196
	s_mov_b32 s44, s33
	s_waitcnt vmcnt(0)
	v_mov_b32_e32 v137, v136
	s_branch .LBB0_339
